# hg<true>: decay vector read after barrier c, S scaling and step-4 fragment fetch spread through the step-3 MFMA stream
# baseline (speedup 1.0000x reference)
; #define LAS __attribute__((address_space(3)))
; template <bool FULL, bool STORE = true>
; __device__ __forceinline__ void hg_item(const Prm& P, LAS unsigned char* lds, int item, int wave) {
;     ...
;         for (int i = 0; i < 8; ++i) { f0[i] = __expf(c0[i]); f1[i] = __expf(c1[i]); ka[i] = 1.0f - f0[i]; kc[i] = 1.0f - f1[i]; t0 += c0[i]; t1 += c1[i]; }
;         *(LAS f32x2*)(lds + HL_TOT + (tg * 128 + k2) * 4) = (f32x2){t0, t1};
;     ...
;                 for (int ks = 0; ks < 8; ++ks) { const bf16x8 a = *(const LAS bf16x8*)(lds + HL_QD + (tb * 32 + l31) * 272 + ks * 32 + lh * 16), bb = *(const LAS bf16x8*)(lds + HL_ST + (vb * 32 + l31) * 272 + ks * 32 + lh * 16);
;                     o = __builtin_amdgcn_mfma_f32_32x32x16_bf16(a, bb, o, 0, 0, 0); }
; #pragma unroll
;                 for (int r = 0; r < 16; ++r) { const int t = tb * 32 + (r & 3) + 8 * (r >> 2) + 4 * lh; *(LAS float*)(lds + HL_OS + t * 528 + (vb * 32 + l31) * 4) = o[r]; }
;             }
;         }
; #pragma unroll
;         for (int g4 = 0; g4 < 4; ++g4) { const f32x4 d = *(const LAS f32x4*)(lds + HL_DC + (kb * 32 + 8 * g4 + 4 * lh) * 4);
; #pragma unroll
;             for (int i = 0; i < 2; ++i)
; #pragma unroll
;                 for (int j = 0; j < 4; ++j) S[i][4 * g4 + j] *= d[j]; }
; #pragma unroll
;         for (int ks = 0; ks < 4; ++ks) { const bf16x8 a = *(const LAS bf16x8*)(lds + HL_KDT + (kb * 32 + l31) * 144 + ks * 32 + lh * 16);
; #pragma unroll
;             for (int i = 0; i < 2; ++i) { const bf16x8 bb = *(const LAS bf16x8*)(lds + HL_IVT + ((vb0 + i) * 32 + l31) * 144 + ks * 32 + lh * 16); S[i] = __builtin_amdgcn_mfma_f32_32x32x16_bf16(a, bb, S[i], 0, 0, 0); } }
.LBB0_839:
	s_mov_b32 s33, 0x800000
	s_add_u32 s86, s86, 0x20000
	s_addc_u32 s87, s87, 0
	v_lshlrev_b32_e32 v104, 16, v52
	v_and_b32_e32 v105, 0xffff0000, v52
	v_lshlrev_b32_e32 v52, 16, v53
	v_and_b32_e32 v53, 0xffff0000, v53
	s_add_u32 s84, s84, 0x10000
	s_addc_u32 s85, s85, 0
	s_cmp_lg_u32 s86, 0x200000
	s_waitcnt lgkmcnt(6)
	v_mfma_f32_32x32x16_bf16 v[32:47], v[172:175], v[176:179], v[32:47]
	ds_read_b128 v[172:175], v151 offset:34944
	ds_read_b128 v[176:179], v152 offset:128
	v_pk_mul_f32 v[0:1], v[0:1], v[78:79]
	v_pk_mul_f32 v[2:3], v[2:3], v[80:81]
	s_waitcnt lgkmcnt(6)
	v_mfma_f32_32x32x16_bf16 v[32:47], v[180:183], v[184:187], v[32:47]
	ds_read_b128 v[180:183], v151 offset:34976
	ds_read_b128 v[184:187], v152 offset:160
	v_pk_mul_f32 v[16:17], v[16:17], v[78:79]
	v_pk_mul_f32 v[18:19], v[18:19], v[80:81]
	s_waitcnt lgkmcnt(6)
	v_mfma_f32_32x32x16_bf16 v[32:47], v[188:191], v[192:195], v[32:47]
	ds_read_b128 v[188:191], v151 offset:35008
	ds_read_b128 v[192:195], v152 offset:192
	v_pk_mul_f32 v[4:5], v[4:5], v[82:83]
	v_pk_mul_f32 v[6:7], v[6:7], v[84:85]
	s_waitcnt lgkmcnt(6)
	v_mfma_f32_32x32x16_bf16 v[32:47], v[196:199], v[200:203], v[32:47]
	ds_read_b128 v[196:199], v151 offset:35040
	ds_read_b128 v[200:203], v152 offset:224
	ds_read_b128 v[204:207], v155 offset:4608
	ds_read_b128 v[208:211], v155 offset:4640
	ds_read_b128 v[212:215], v155 offset:4672
	ds_read_b128 v[216:219], v155 offset:4704
	v_pk_mul_f32 v[20:21], v[20:21], v[82:83]
	v_pk_mul_f32 v[22:23], v[22:23], v[84:85]
	s_waitcnt lgkmcnt(10)
	v_mfma_f32_32x32x16_bf16 v[32:47], v[172:175], v[176:179], v[32:47]
	v_pk_mul_f32 v[8:9], v[8:9], v[86:87]
	v_pk_mul_f32 v[10:11], v[10:11], v[88:89]
	ds_read_b128 v[172:175], v154 offset:52224
	ds_read_b128 v[176:179], v154 offset:52256
	s_waitcnt lgkmcnt(10)
	v_mfma_f32_32x32x16_bf16 v[32:47], v[180:183], v[184:187], v[32:47]
	v_pk_mul_f32 v[24:25], v[24:25], v[86:87]
	v_pk_mul_f32 v[26:27], v[26:27], v[88:89]
	ds_read_b128 v[180:183], v154 offset:52288
	ds_read_b128 v[184:187], v154 offset:52320
	s_waitcnt lgkmcnt(10)
	v_mfma_f32_32x32x16_bf16 v[32:47], v[188:191], v[192:195], v[32:47]
	v_pk_mul_f32 v[12:13], v[12:13], v[90:91]
	v_pk_mul_f32 v[14:15], v[14:15], v[92:93]
	ds_read_b128 v[188:191], v155
	ds_read_b128 v[192:195], v155 offset:32
	s_waitcnt lgkmcnt(10)
	v_mfma_f32_32x32x16_bf16 v[32:47], v[196:199], v[200:203], v[32:47]
	v_pk_mul_f32 v[28:29], v[28:29], v[90:91]
	v_pk_mul_f32 v[30:31], v[30:31], v[92:93]
	ds_read_b128 v[196:199], v155 offset:64
	ds_read_b128 v[200:203], v155 offset:96
	s_nop 11
	ds_write2_b32 v153, v32, v33 offset1:132
	v_add_u32_e32 v32, 0x400, v153
	ds_write2_b32 v32, v34, v35 offset0:8 offset1:140
	v_add_u32_e32 v32, 0x1000, v153
	ds_write2_b32 v32, v36, v37 offset0:32 offset1:164
	v_add_u32_e32 v32, 0x1400, v153
	ds_write2_b32 v32, v38, v39 offset0:40 offset1:172
	v_add_u32_e32 v32, 0x2000, v153
	ds_write2_b32 v32, v40, v41 offset0:64 offset1:196
	v_add_u32_e32 v32, 0x2400, v153
	ds_write2_b32 v32, v42, v43 offset0:72 offset1:204
	v_add_u32_e32 v32, 0x3000, v153
	ds_write2_b32 v32, v44, v45 offset0:96 offset1:228
	v_add_u32_e32 v32, 0x3400, v153
	ds_write2_b32 v32, v46, v47 offset0:104 offset1:236
	s_waitcnt vmcnt(18)
	v_cvt_f32_f16_e32 v78, v240
	v_cvt_f32_f16_sdwa v79, v240 dst_sel:DWORD dst_unused:UNUSED_PAD src0_sel:WORD_1
	v_cvt_f32_f16_e32 v80, v241
	v_cvt_f32_f16_sdwa v81, v241 dst_sel:DWORD dst_unused:UNUSED_PAD src0_sel:WORD_1
	v_cvt_f32_f16_e32 v82, v242
	v_cvt_f32_f16_sdwa v83, v242 dst_sel:DWORD dst_unused:UNUSED_PAD src0_sel:WORD_1
	v_cvt_f32_f16_e32 v84, v243
	v_cvt_f32_f16_sdwa v85, v243 dst_sel:DWORD dst_unused:UNUSED_PAD src0_sel:WORD_1
	v_cvt_f32_f16_e32 v86, v244
	v_cvt_f32_f16_sdwa v87, v244 dst_sel:DWORD dst_unused:UNUSED_PAD src0_sel:WORD_1
	v_cvt_f32_f16_e32 v88, v245
	v_cvt_f32_f16_sdwa v89, v245 dst_sel:DWORD dst_unused:UNUSED_PAD src0_sel:WORD_1
	v_cvt_f32_f16_e32 v90, v246
	v_cvt_f32_f16_sdwa v91, v246 dst_sel:DWORD dst_unused:UNUSED_PAD src0_sel:WORD_1
	v_cvt_f32_f16_e32 v92, v247
	v_cvt_f32_f16_sdwa v93, v247 dst_sel:DWORD dst_unused:UNUSED_PAD src0_sel:WORD_1
	s_nop 0
	v_pk_add_f32 v[32:33], v[78:79], 0 op_sel_hi:[1,0]
	v_pk_add_f32 v[32:33], v[32:33], v[80:81]
	v_pk_add_f32 v[32:33], v[32:33], v[82:83]
	v_pk_add_f32 v[32:33], v[32:33], v[84:85]
	v_pk_add_f32 v[32:33], v[32:33], v[86:87]
	v_pk_add_f32 v[32:33], v[32:33], v[88:89]
	v_pk_add_f32 v[32:33], v[32:33], v[90:91]
	v_pk_add_f32 v[32:33], v[32:33], v[92:93]
	v_add_u32_e32 v36, s60, v126
	ds_write_b64 v36, v[32:33]
	s_waitcnt lgkmcnt(0)
	s_barrier
; #define LAS __attribute__((address_space(3)))
; __device__ __forceinline__ unsigned pk2(float lo, float hi) { typedef float f2v __attribute__((ext_vector_type(2))); typedef __bf16 b2v __attribute__((ext_vector_type(2))); const f2v v = {lo, hi}; const b2v b = __builtin_convertvector(v, b2v); return __builtin_bit_cast(unsigned, b); }
; template <bool FULL, bool STORE = true>
; __device__ __forceinline__ void hg_item(const Prm& P, LAS unsigned char* lds, int item, int wave) {
;     ...
;         for (int ks = 0; ks < 4; ++ks) { const bf16x8 a = *(const LAS bf16x8*)(lds + HL_KDT + (kb * 32 + l31) * 144 + ks * 32 + lh * 16);
; #pragma unroll
;             for (int i = 0; i < 2; ++i) { const bf16x8 bb = *(const LAS bf16x8*)(lds + HL_IVT + ((vb0 + i) * 32 + l31) * 144 + ks * 32 + lh * 16); S[i] = __builtin_amdgcn_mfma_f32_32x32x16_bf16(a, bb, S[i], 0, 0, 0); } }
;         if (FULL) {
;             __syncthreads();
; #pragma unroll
;             for (int i = 0; i < 2; ++i)
; #pragma unroll
;                 for (int g4 = 0; g4 < 4; ++g4) { u32x2 w; w.x = pk2(S[i][4 * g4], S[i][4 * g4 + 1]); w.y = pk2(S[i][4 * g4 + 2], S[i][4 * g4 + 3]);
;                     *(LAS u32x2*)(lds + HL_ST + ((vb0 + i) * 32 + l31) * 272 + (kb * 32 + 8 * g4 + 4 * lh) * 2) = w; }
;             { const int t = tid >> 3, vs = (tid & 7) * 16; float o[16]; float ss = 0.f;
; #pragma unroll
;                 for (int q4 = 0; q4 < 4; ++q4) { const f32x4 x4 = *(const LAS f32x4*)(lds + HL_OS + t * 528 + (vs + 4 * q4) * 4);
; #pragma unroll
;                     for (int j = 0; j < 4; ++j) { o[4 * q4 + j] = x4[j]; ss += x4[j] * x4[j]; } }
;                 ss += __shfl_xor(ss, 1); ss += __shfl_xor(ss, 2); ss += __shfl_xor(ss, 4);
;                 const float r = rsqrtf(ss * (1.0f / 128.0f) + EPS);
;                 const size_t oo = (row0 + t) * 1024 + h * 128 + vs; const float* gn = P.in[I_HGNG] + h * 128 + vs;
;                 float g0[8], g1[8]; unpack8(gcur0, g0); unpack8(gcur1, g1);
;                 float w0[8], w1[8];
; #pragma unroll
;                 for (int j = 0; j < 8; ++j) { w0[j] = o[j] * r * gn[j] * g0[j]; w1[j] = o[8 + j] * r * gn[8 + j] * g1[j]; }
;                 if (STORE) { *(u32x4*)(AHG + oo) = pack8(w0); *(u32x4*)(AHG + oo + 8) = pack8(w1); }
;             }
	ds_read_b128 v[66:69], v157
	ds_read_b128 v[36:39], v157 offset:16
	ds_read_b128 v[44:47], v157 offset:32
	ds_read_b128 v[32:35], v157 offset:48
	s_waitcnt lgkmcnt(3)
	v_mul_f32_e32 v64, v67, v67
	v_mfma_f32_32x32x16_bf16 v[0:15], v[172:175], v[188:191], v[0:15]
	v_fmac_f32_e32 v64, v66, v66
	v_fmac_f32_e32 v64, v68, v68
	v_fmac_f32_e32 v64, v69, v69
	s_waitcnt lgkmcnt(2)
	v_fmac_f32_e32 v64, v36, v36
	v_fmac_f32_e32 v64, v37, v37
	v_fmac_f32_e32 v64, v38, v38
	v_fmac_f32_e32 v64, v39, v39
	v_mfma_f32_32x32x16_bf16 v[16:31], v[172:175], v[204:207], v[16:31]
	s_waitcnt lgkmcnt(1)
	v_pk_mul_f32 v[42:43], v[44:45], v[44:45]
	v_pk_mul_f32 v[40:41], v[46:47], v[46:47]
	v_add_f32_e32 v42, v42, v64
	v_add_f32_e32 v42, v43, v42
	v_add_f32_e32 v40, v40, v42
	v_add_f32_e32 v64, v41, v40
	s_waitcnt lgkmcnt(0)
	s_barrier
	v_pk_mul_f32 v[42:43], v[32:33], v[32:33]
	v_mfma_f32_32x32x16_bf16 v[0:15], v[176:179], v[192:195], v[0:15]
	v_pk_mul_f32 v[40:41], v[34:35], v[34:35]
	v_add_f32_e32 v42, v42, v64
	v_add_f32_e32 v42, v43, v42
	v_add_f32_e32 v40, v40, v42
	v_add_f32_e32 v40, v41, v40
	s_nop 1
	v_add_f32_dpp v40, v40, v40 quad_perm:[1,0,3,2] row_mask:0xf bank_mask:0xf
	s_nop 1
	v_add_f32_dpp v40, v40, v40 quad_perm:[2,3,0,1] row_mask:0xf bank_mask:0xf
	v_mfma_f32_32x32x16_bf16 v[16:31], v[176:179], v[208:211], v[16:31]
	s_nop 1
	v_add_f32_dpp v40, v40, v40 row_half_mirror row_mask:0xf bank_mask:0xf
	v_fmamk_f32 v40, v40, 0x3c000000, v109
	v_cmp_gt_f32_e32 vcc, s33, v40
	v_mul_f32_e32 v41, 0x4b800000, v40
	s_mov_b32 s33, 0x7400000
	v_cndmask_b32_e32 v40, v40, v41, vcc
	v_rsq_f32_e32 v40, v40
	s_nop 0
	v_mul_f32_e32 v41, 0x45800000, v40
	v_mfma_f32_32x32x16_bf16 v[0:15], v[180:183], v[196:199], v[0:15]
	v_cndmask_b32_e32 v74, v40, v41, vcc
	v_pk_mul_f32 v[106:107], v[66:67], v[74:75] op_sel_hi:[1,0]
	v_pk_mul_f32 v[46:47], v[46:47], v[74:75] op_sel_hi:[1,0]
	v_pk_mul_f32 v[36:37], v[36:37], v[74:75] op_sel_hi:[1,0]
	v_pk_mul_f32 v[32:33], v[32:33], v[74:75] op_sel_hi:[1,0]
	v_pk_mul_f32 v[44:45], v[44:45], v[74:75] op_sel_hi:[1,0]
	v_pk_mul_f32 v[38:39], v[38:39], v[74:75] op_sel_hi:[1,0]
	v_mfma_f32_32x32x16_bf16 v[16:31], v[180:183], v[212:215], v[16:31]
	v_pk_mul_f32 v[34:35], v[34:35], v[74:75] op_sel_hi:[1,0]
	s_waitcnt vmcnt(0)
	v_pk_mul_f32 v[32:33], v[224:225], v[32:33]
	v_pk_mul_f32 v[46:47], v[230:231], v[46:47]
	v_pk_mul_f32 v[36:37], v[232:233], v[36:37]
	v_pk_mul_f32 v[106:107], v[236:237], v[106:107]
	v_pk_mul_f32 v[44:45], v[228:229], v[44:45]
	v_pk_mul_f32 v[104:105], v[106:107], v[104:105]
	v_mfma_f32_32x32x16_bf16 v[0:15], v[184:187], v[200:203], v[0:15]
	v_lshlrev_b32_e32 v106, 16, v48
	v_and_b32_e32 v107, 0xffff0000, v48
	v_lshlrev_b32_e32 v48, 16, v49
	v_and_b32_e32 v49, 0xffff0000, v49
	v_pk_mul_f32 v[46:47], v[46:47], v[48:49]
	v_lshlrev_b32_e32 v48, 16, v54
	v_and_b32_e32 v49, 0xffff0000, v54
	v_mfma_f32_32x32x16_bf16 v[16:31], v[184:187], v[216:219], v[16:31]
	v_pk_mul_f32 v[36:37], v[36:37], v[48:49]
	v_lshlrev_b32_e32 v48, 16, v50
	v_and_b32_e32 v49, 0xffff0000, v50
	v_pk_mul_f32 v[64:65], v[68:69], v[74:75] op_sel_hi:[1,0]
	v_pk_mul_f32 v[40:41], v[32:33], v[48:49]
	v_lshlrev_b32_e32 v32, 16, v55
	v_and_b32_e32 v33, 0xffff0000, v55
	v_pk_mul_f32 v[38:39], v[234:235], v[38:39]
	v_pk_mul_f32 v[64:65], v[238:239], v[64:65]
	v_pk_mul_f32 v[38:39], v[38:39], v[32:33]
	v_lshlrev_b32_e32 v32, 16, v51
	v_and_b32_e32 v33, 0xffff0000, v51
	v_pk_mul_f32 v[34:35], v[226:227], v[34:35]
	v_pk_mul_f32 v[52:53], v[64:65], v[52:53]
	v_pk_mul_f32 v[42:43], v[34:35], v[32:33]
	v_cvt_pk_bf16_f32 v34, v36, v37
	v_add_co_u32_e32 v36, vcc, s33, v102
	v_pk_mul_f32 v[44:45], v[44:45], v[106:107]
	v_cvt_pk_bf16_f32 v32, v104, v105
	v_cvt_pk_bf16_f32 v33, v52, v53
	v_cvt_pk_bf16_f32 v35, v38, v39
	v_addc_co_u32_e32 v37, vcc, 0, v103, vcc
	v_mov_b64_e32 v[52:53], v[56:57]
	v_mov_b64_e32 v[48:49], v[60:61]
	global_store_dwordx4 v[36:37], v[32:35], off
	v_mov_b64_e32 v[54:55], v[58:59]
	v_mov_b64_e32 v[50:51], v[62:63]
	v_cvt_pk_bf16_f32 v32, v44, v45
	v_cvt_pk_bf16_f32 v33, v46, v47
	v_cvt_pk_bf16_f32 v34, v40, v41
	v_cvt_pk_bf16_f32 v35, v42, v43
	global_store_dwordx4 v[36:37], v[32:35], off offset:16
	s_nop 8
	v_cvt_pk_bf16_f32 v32, v0, v1
	v_cvt_pk_bf16_f32 v33, v2, v3
	v_cvt_pk_bf16_f32 v34, v4, v5
	v_cvt_pk_bf16_f32 v35, v6, v7
	ds_write2_b64 v156, v[32:33], v[34:35] offset1:2
	v_cvt_pk_bf16_f32 v32, v8, v9
	v_cvt_pk_bf16_f32 v33, v10, v11
	v_cvt_pk_bf16_f32 v34, v12, v13
	v_cvt_pk_bf16_f32 v35, v14, v15
	ds_write2_b64 v156, v[32:33], v[34:35] offset0:4 offset1:6
	v_cvt_pk_bf16_f32 v32, v16, v17
	v_cvt_pk_bf16_f32 v33, v18, v19
	v_cvt_pk_bf16_f32 v34, v20, v21
	v_cvt_pk_bf16_f32 v35, v22, v23
	v_add_u32_e32 v36, 0x2000, v156
	ds_write2_b64 v36, v[32:33], v[34:35] offset0:64 offset1:66
	v_cvt_pk_bf16_f32 v32, v24, v25
	v_cvt_pk_bf16_f32 v33, v26, v27
	v_cvt_pk_bf16_f32 v34, v28, v29
	v_cvt_pk_bf16_f32 v35, v30, v31
	ds_write2_b64 v36, v[32:33], v[34:35] offset0:68 offset1:70
	s_cbranch_scc0 .LBB0_821

; #define LAS __attribute__((address_space(3)))
; template <bool FULL, bool STORE = true>
; __device__ __forceinline__ void hg_item(const Prm& P, LAS unsigned char* lds, int item, int wave) {
;     ...
;             { const int tb = wave >> 2, vb = wave & 3; f32x16 o;
; #pragma unroll
;                 for (int r = 0; r < 16; ++r) o[r] = 0.f;
; #pragma unroll
;                 for (int ks = 0; ks < 4; ++ks) { if (ks < 2 || tb) { const bf16x8 a = *(const LAS bf16x8*)(lds + HL_PP + (tb * 32 + l31) * 144 + ks * 32 + lh * 16), bb = *(const LAS bf16x8*)(lds + HL_IVT + (vb * 32 + l31) * 144 + ks * 32 + lh * 16);
;                         o = __builtin_amdgcn_mfma_f32_32x32x16_bf16(a, bb, o, 0, 0, 0); } }
; #pragma unroll
;                 for (int ks = 0; ks < 8; ++ks) { const bf16x8 a = *(const LAS bf16x8*)(lds + HL_QD + (tb * 32 + l31) * 272 + ks * 32 + lh * 16), bb = *(const LAS bf16x8*)(lds + HL_ST + (vb * 32 + l31) * 272 + ks * 32 + lh * 16);
;                     o = __builtin_amdgcn_mfma_f32_32x32x16_bf16(a, bb, o, 0, 0, 0); }
; #pragma unroll
;                 for (int r = 0; r < 16; ++r) { const int t = tb * 32 + (r & 3) + 8 * (r >> 2) + 4 * lh; *(LAS float*)(lds + HL_OS + t * 528 + (vb * 32 + l31) * 4) = o[r]; }
;             }
;         }
; #pragma unroll
;         for (int g4 = 0; g4 < 4; ++g4) { const f32x4 d = *(const LAS f32x4*)(lds + HL_DC + (kb * 32 + 8 * g4 + 4 * lh) * 4);
.LBB0_846:
	v_add_u32_e32 v220, s96, v128
	s_waitcnt lgkmcnt(0)
	s_barrier
	ds_read_b128 v[78:81], v220
	ds_read_b128 v[82:85], v220 offset:32
	ds_read_b128 v[86:89], v220 offset:64
	ds_read_b128 v[90:93], v220 offset:96
	ds_read_b128 v[204:207], v158
	ds_read_b128 v[208:211], v159
	ds_read_b128 v[212:215], v158 offset:32
	ds_read_b128 v[216:219], v159 offset:32
	s_andn2_b64 vcc, exec, s[4:5]
	s_cbranch_vccnz .Lhgt_tb0
	ds_read_b128 v[188:191], v158 offset:64
	ds_read_b128 v[192:195], v159 offset:64
	ds_read_b128 v[196:199], v158 offset:96
	ds_read_b128 v[200:203], v159 offset:96
	ds_read_b128 v[172:175], v151 offset:34816
	ds_read_b128 v[176:179], v152
	ds_read_b128 v[180:183], v151 offset:34848
	ds_read_b128 v[184:187], v152 offset:32
	s_waitcnt lgkmcnt(10)
	v_mfma_f32_32x32x16_bf16 v[32:47], v[204:207], v[208:211], 0
	s_waitcnt lgkmcnt(8)
	v_mfma_f32_32x32x16_bf16 v[32:47], v[212:215], v[216:219], v[32:47]
	s_waitcnt lgkmcnt(6)
	v_mfma_f32_32x32x16_bf16 v[32:47], v[188:191], v[192:195], v[32:47]
	ds_read_b128 v[188:191], v151 offset:34880
	ds_read_b128 v[192:195], v152 offset:64
	s_waitcnt lgkmcnt(6)
	v_mfma_f32_32x32x16_bf16 v[32:47], v[196:199], v[200:203], v[32:47]
	ds_read_b128 v[196:199], v151 offset:34912
	ds_read_b128 v[200:203], v152 offset:96
	s_branch .LBB0_839
